# baseline (speedup 1.0000x reference)
; DEV void mod_job(const Params& p, int job, float* sm) {
;     ...
;     for (int k = 0; k < 256; ++k) {
;         const float wv = w[(size_t)k * 6144];
; #pragma unroll
;         for (int v = 0; v < 9; ++v) acc[v] += sc[v * 1024 + kq * 256 + k] * wv;
;     }
.LBB0_2642:
	v_lshl_add_u64 v[92:93], v[68:69], 0, s[4:5]
	v_add_co_u32_e32 v96, vcc, s33, v92
	ds_read_b128 v[8:11], v81
	ds_read_b128 v[0:3], v81 offset:16
	ds_read_b128 v[4:7], v81 offset:4096
	ds_read_b128 v[12:15], v81 offset:4112
	ds_read_b128 v[50:53], v81 offset:8192
	ds_read_b128 v[38:41], v81 offset:8208
	ds_read_b128 v[24:27], v81 offset:12288
	ds_read_b128 v[16:19], v81 offset:12304
	ds_read_b128 v[54:57], v81 offset:16384
	ds_read_b128 v[42:45], v81 offset:16400
	ds_read_b128 v[28:31], v81 offset:20480
	ds_read_b128 v[20:23], v81 offset:20496
	ds_read_b128 v[58:61], v81 offset:24576
	ds_read_b128 v[62:65], v81 offset:24592
	ds_read_b128 v[46:49], v81 offset:28672
	ds_read_b128 v[34:37], v81 offset:28688
	v_addc_co_u32_e32 v97, vcc, 0, v93, vcc
	v_add_co_u32_e32 v98, vcc, s36, v92
	ds_read_b128 v[84:87], v81 offset:32768
	ds_read_b128 v[88:91], v81 offset:32784
	v_addc_co_u32_e32 v99, vcc, 0, v93, vcc
	v_add_co_u32_e32 v100, vcc, s24, v92
	global_load_dword v94, v[92:93], off
	s_nop 0
	v_addc_co_u32_e32 v101, vcc, 0, v93, vcc
	v_add_co_u32_e32 v102, vcc, s37, v92
	s_mov_b32 s7, 0x1e000
	s_nop 0
	v_addc_co_u32_e32 v103, vcc, 0, v93, vcc
	v_add_co_u32_e32 v104, vcc, s7, v92
	s_mov_b32 s7, 0x2a000
	s_nop 0
	v_addc_co_u32_e32 v105, vcc, 0, v93, vcc
	v_add_co_u32_e32 v106, vcc, s25, v92
	global_load_dword v96, v[96:97], off
	s_nop 0
	global_load_dword v98, v[98:99], off
	s_nop 0
	global_load_dword v100, v[100:101], off
	s_nop 0
	global_load_dword v102, v[102:103], off
	s_nop 0
	global_load_dword v104, v[104:105], off
	v_addc_co_u32_e32 v107, vcc, 0, v93, vcc
	v_add_co_u32_e32 v92, vcc, s7, v92
	s_waitcnt lgkmcnt(0)
	v_mov_b32_e32 v108, v8
	v_addc_co_u32_e32 v93, vcc, 0, v93, vcc
	global_load_dword v106, v[106:107], off
	s_nop 0
	global_load_dword v92, v[92:93], off
	v_mov_b32_e32 v109, v4
	v_mov_b32_e32 v4, v9
	v_mov_b32_e32 v8, v10
	v_mov_b32_e32 v9, v6
	v_mov_b32_e32 v6, v11
	v_mov_b32_e32 v10, v50
	v_mov_b32_e32 v11, v24
	v_mov_b32_e32 v24, v51
	v_mov_b32_e32 v50, v52
	v_mov_b32_e32 v51, v26
	v_mov_b32_e32 v26, v53
	v_mov_b32_e32 v52, v54
	v_mov_b32_e32 v53, v28
	v_mov_b32_e32 v28, v55
	v_mov_b32_e32 v54, v56
	v_mov_b32_e32 v55, v30
	v_mov_b32_e32 v30, v57
	v_mov_b32_e32 v56, v58
	v_mov_b32_e32 v57, v46
	v_mov_b32_e32 v46, v59
	v_mov_b32_e32 v58, v60
	v_mov_b32_e32 v59, v48
	v_mov_b32_e32 v48, v61
	v_mov_b32_e32 v60, v0
	v_mov_b32_e32 v61, v12
	v_mov_b32_e32 v12, v1
	v_mov_b32_e32 v0, v2
	v_mov_b32_e32 v1, v14
	v_mov_b32_e32 v14, v3
	v_mov_b32_e32 v2, v38
	v_mov_b32_e32 v3, v16
	v_mov_b32_e32 v16, v39
	v_mov_b32_e32 v38, v40
	v_mov_b32_e32 v39, v18
	v_mov_b32_e32 v18, v41
	v_mov_b32_e32 v40, v42
	v_mov_b32_e32 v41, v20
	v_mov_b32_e32 v20, v43
	v_mov_b32_e32 v42, v44
	v_mov_b32_e32 v43, v22
	v_mov_b32_e32 v22, v45
	v_mov_b32_e32 v44, v62
	v_mov_b32_e32 v45, v34
	v_mov_b32_e32 v34, v63
	v_mov_b32_e32 v62, v64
	v_mov_b32_e32 v63, v36
	v_mov_b32_e32 v36, v65
	s_add_u32 s4, s4, 0x30000
	s_addc_u32 s5, s5, 0
	v_add_u32_e32 v81, 32, v81
	s_cmp_eq_u32 s4, 0x600000
	s_waitcnt vmcnt(0)
	v_pk_fma_f32 v[64:65], v[94:95], v[108:109], v[70:71] op_sel_hi:[0,1,1]
	v_pk_fma_f32 v[10:11], v[94:95], v[10:11], v[72:73] op_sel_hi:[0,1,1]
	v_pk_fma_f32 v[52:53], v[94:95], v[52:53], v[74:75] op_sel_hi:[0,1,1]
	v_pk_fma_f32 v[56:57], v[94:95], v[56:57], v[76:77] op_sel_hi:[0,1,1]
	v_fmac_f32_e32 v82, v94, v84
	v_pk_fma_f32 v[4:5], v[96:97], v[4:5], v[64:65] op_sel_hi:[0,1,1]
	v_pk_fma_f32 v[10:11], v[96:97], v[24:25], v[10:11] op_sel_hi:[0,1,1]
	v_pk_fma_f32 v[24:25], v[96:97], v[28:29], v[52:53] op_sel_hi:[0,1,1]
	v_pk_fma_f32 v[28:29], v[96:97], v[46:47], v[56:57] op_sel_hi:[0,1,1]
	v_fmac_f32_e32 v82, v96, v85
	v_pk_fma_f32 v[4:5], v[98:99], v[8:9], v[4:5] op_sel_hi:[0,1,1]
	v_pk_fma_f32 v[8:9], v[98:99], v[50:51], v[10:11] op_sel_hi:[0,1,1]
	v_pk_fma_f32 v[10:11], v[98:99], v[54:55], v[24:25] op_sel_hi:[0,1,1]
	v_pk_fma_f32 v[24:25], v[98:99], v[58:59], v[28:29] op_sel_hi:[0,1,1]
	v_fmac_f32_e32 v82, v98, v86
	v_pk_fma_f32 v[4:5], v[100:101], v[6:7], v[4:5] op_sel_hi:[0,1,1]
	v_pk_fma_f32 v[6:7], v[100:101], v[26:27], v[8:9] op_sel_hi:[0,1,1]
	v_pk_fma_f32 v[8:9], v[100:101], v[30:31], v[10:11] op_sel_hi:[0,1,1]
	v_pk_fma_f32 v[10:11], v[100:101], v[48:49], v[24:25] op_sel_hi:[0,1,1]
	v_fmac_f32_e32 v82, v100, v87
	v_pk_fma_f32 v[4:5], v[102:103], v[60:61], v[4:5] op_sel_hi:[0,1,1]
	v_pk_fma_f32 v[2:3], v[102:103], v[2:3], v[6:7] op_sel_hi:[0,1,1]
	v_pk_fma_f32 v[6:7], v[102:103], v[40:41], v[8:9] op_sel_hi:[0,1,1]
	v_pk_fma_f32 v[8:9], v[102:103], v[44:45], v[10:11] op_sel_hi:[0,1,1]
	v_fmac_f32_e32 v82, v102, v88
	v_pk_fma_f32 v[4:5], v[104:105], v[12:13], v[4:5] op_sel_hi:[0,1,1]
	v_pk_fma_f32 v[2:3], v[104:105], v[16:17], v[2:3] op_sel_hi:[0,1,1]
	v_pk_fma_f32 v[6:7], v[104:105], v[20:21], v[6:7] op_sel_hi:[0,1,1]
	v_pk_fma_f32 v[8:9], v[104:105], v[34:35], v[8:9] op_sel_hi:[0,1,1]
	v_fmac_f32_e32 v82, v104, v89
	s_waitcnt lgkmcnt(0)
	v_pk_fma_f32 v[0:1], v[106:107], v[0:1], v[4:5] op_sel_hi:[0,1,1]
	v_pk_fma_f32 v[2:3], v[106:107], v[38:39], v[2:3] op_sel_hi:[0,1,1]
	v_pk_fma_f32 v[4:5], v[106:107], v[42:43], v[6:7] op_sel_hi:[0,1,1]
	v_pk_fma_f32 v[6:7], v[106:107], v[62:63], v[8:9] op_sel_hi:[0,1,1]
	v_fmac_f32_e32 v82, v106, v90
	v_pk_fma_f32 v[70:71], v[92:93], v[14:15], v[0:1] op_sel_hi:[0,1,1]
	v_pk_fma_f32 v[72:73], v[92:93], v[18:19], v[2:3] op_sel_hi:[0,1,1]
	v_pk_fma_f32 v[74:75], v[92:93], v[22:23], v[4:5] op_sel_hi:[0,1,1]
	v_pk_fma_f32 v[76:77], v[92:93], v[36:37], v[6:7] op_sel_hi:[0,1,1]
	v_fmac_f32_e32 v82, v92, v91
	s_cbranch_scc0 .LBB0_2642
;     __device__ __forceinline__ float* mod() const { return (float*)(ws + OFF_mod); }
; DEV void mod_job(const Params& p, int job, float* sm) {
;     ...
; #pragma unroll
;     for (int v = 0; v < 9; ++v) red[(kq * 9 + v) * 64 + c] = acc[v];
;     __syncthreads();
;     if (kq == 0) {
; #pragma unroll
;         for (int v = 0; v < 9; ++v)
;             p.mod()[(size_t)(l * 9 + v) * 6144 + col] = red[(0 * 9 + v) * 64 + c] + red[(1 * 9 + v) * 64 + c] + red[(2 * 9 + v) * 64 + c] + red[(3 * 9 + v) * 64 + c] + p.b_ada[l * 6144 + col];
;     }
	s_movk_i32 s4, 0x900
	v_lshlrev_b32_e32 v0, 2, v80
	v_mul_lo_u32 v1, v32, s4
	v_add3_u32 v0, 0, v0, v1
	v_cmp_gt_u32_e32 vcc, 64, v79
	ds_write2st64_b32 v0, v70, v71 offset0:144 offset1:145
	ds_write2st64_b32 v0, v72, v73 offset0:146 offset1:147
	ds_write2st64_b32 v0, v74, v75 offset0:148 offset1:149
	ds_write2st64_b32 v0, v76, v77 offset0:150 offset1:151
	ds_write_b32 v0, v82 offset:38912
	s_waitcnt lgkmcnt(0)
	s_barrier
	s_and_saveexec_b64 s[4:5], vcc
	s_cbranch_execz .LBB0_2633
	s_mul_i32 s7, s6, 0x1800
	v_add_u32_e32 v0, s7, v66
	v_ashrrev_i32_e32 v1, 31, v0
	v_lshl_add_u64 v[0:1], v[0:1], 2, s[18:19]
	flat_load_dword v6, v[0:1]
	ds_read_b32 v7, v78 offset:36864
	ds_read_b32 v8, v78 offset:39168
	ds_read_b32 v9, v78 offset:41472
	ds_read_b32 v10, v78 offset:43776
	s_mul_i32 s8, s6, 9
	v_lshl_add_u64 v[2:3], v[66:67], 2, s[0:1]
	s_waitcnt lgkmcnt(0)
	v_add_f32_e32 v7, v7, v8
	v_add_f32_e32 v7, v7, v9
	v_add_f32_e32 v7, v7, v10
	v_mad_i64_i32 v[4:5], s[6:7], s8, v204, v[2:3]
	s_add_i32 s6, s8, 1
	s_waitcnt vmcnt(0)
	v_add_f32_e32 v6, v7, v6
	flat_store_dword v[4:5], v6
	flat_load_dword v6, v[0:1]
	ds_read_b32 v7, v78 offset:37120
	ds_read_b32 v8, v78 offset:39424
	ds_read_b32 v9, v78 offset:41728
	ds_read_b32 v10, v78 offset:44032
	v_mad_i64_i32 v[4:5], s[6:7], s6, v204, v[2:3]
	s_waitcnt lgkmcnt(0)
	v_add_f32_e32 v7, v7, v8
	v_add_f32_e32 v7, v7, v9
	v_add_f32_e32 v7, v7, v10
	s_add_i32 s6, s8, 2
	s_waitcnt vmcnt(0)
	v_add_f32_e32 v6, v7, v6
	flat_store_dword v[4:5], v6
	flat_load_dword v6, v[0:1]
	ds_read_b32 v7, v78 offset:37376
	ds_read_b32 v8, v78 offset:39680
	ds_read_b32 v9, v78 offset:41984
	ds_read_b32 v10, v78 offset:44288
	v_mad_i64_i32 v[4:5], s[6:7], s6, v204, v[2:3]
	s_waitcnt lgkmcnt(0)
	v_add_f32_e32 v7, v7, v8
	v_add_f32_e32 v7, v7, v9
	v_add_f32_e32 v7, v7, v10
	s_add_i32 s6, s8, 3
	s_waitcnt vmcnt(0)
	v_add_f32_e32 v6, v7, v6
	flat_store_dword v[4:5], v6
	flat_load_dword v6, v[0:1]
	ds_read_b32 v7, v78 offset:37632
	ds_read_b32 v8, v78 offset:39936
	ds_read_b32 v9, v78 offset:42240
	ds_read_b32 v10, v78 offset:44544
	v_mad_i64_i32 v[4:5], s[6:7], s6, v204, v[2:3]
	s_waitcnt lgkmcnt(0)
	v_add_f32_e32 v7, v7, v8
	v_add_f32_e32 v7, v7, v9
	v_add_f32_e32 v7, v7, v10
	s_add_i32 s6, s8, 4
	s_waitcnt vmcnt(0)
	v_add_f32_e32 v6, v7, v6
	flat_store_dword v[4:5], v6
	flat_load_dword v6, v[0:1]
	ds_read_b32 v7, v78 offset:37888
	ds_read_b32 v8, v78 offset:40192
	ds_read_b32 v9, v78 offset:42496
	ds_read_b32 v10, v78 offset:44800
	v_mad_i64_i32 v[4:5], s[6:7], s6, v204, v[2:3]
	s_waitcnt lgkmcnt(0)
	v_add_f32_e32 v7, v7, v8
	v_add_f32_e32 v7, v7, v9
	v_add_f32_e32 v7, v7, v10
	s_add_i32 s6, s8, 5
	s_waitcnt vmcnt(0)
	v_add_f32_e32 v6, v7, v6
	flat_store_dword v[4:5], v6
	flat_load_dword v6, v[0:1]
	ds_read_b32 v7, v78 offset:38144
	ds_read_b32 v8, v78 offset:40448
	ds_read_b32 v9, v78 offset:42752
	ds_read_b32 v10, v78 offset:45056
	v_mad_i64_i32 v[4:5], s[6:7], s6, v204, v[2:3]
	s_waitcnt lgkmcnt(0)
	v_add_f32_e32 v7, v7, v8
	v_add_f32_e32 v7, v7, v9
	v_add_f32_e32 v7, v7, v10
	s_add_i32 s6, s8, 6
	s_waitcnt vmcnt(0)
	v_add_f32_e32 v6, v7, v6
	flat_store_dword v[4:5], v6
	flat_load_dword v6, v[0:1]
	ds_read_b32 v7, v78 offset:38400
	ds_read_b32 v8, v78 offset:40704
	ds_read_b32 v9, v78 offset:43008
	ds_read_b32 v10, v78 offset:45312
	v_mad_i64_i32 v[4:5], s[6:7], s6, v204, v[2:3]
	s_waitcnt lgkmcnt(0)
	v_add_f32_e32 v7, v7, v8
	v_add_f32_e32 v7, v7, v9
	v_add_f32_e32 v7, v7, v10
	s_add_i32 s6, s8, 7
	s_add_i32 s8, s8, 8
	s_waitcnt vmcnt(0)
	v_add_f32_e32 v6, v7, v6
	flat_store_dword v[4:5], v6
	flat_load_dword v6, v[0:1]
	ds_read_b32 v7, v78 offset:38656
	ds_read_b32 v8, v78 offset:40960
	ds_read_b32 v9, v78 offset:43264
	ds_read_b32 v10, v78 offset:45568
	v_mad_i64_i32 v[4:5], s[6:7], s6, v204, v[2:3]
	s_waitcnt lgkmcnt(0)
	v_add_f32_e32 v7, v7, v8
	v_add_f32_e32 v7, v7, v9
	v_add_f32_e32 v7, v7, v10
	s_waitcnt vmcnt(0)
	v_add_f32_e32 v6, v7, v6
	flat_store_dword v[4:5], v6
	flat_load_dword v0, v[0:1]
	ds_read_b32 v1, v78 offset:38912
	ds_read_b32 v4, v78 offset:41216
	ds_read_b32 v5, v78 offset:43520
	ds_read_b32 v6, v78 offset:45824
	s_waitcnt lgkmcnt(0)
	v_add_f32_e32 v1, v1, v4
	v_add_f32_e32 v1, v1, v5
	v_add_f32_e32 v1, v1, v6
	s_waitcnt vmcnt(0)
	v_add_f32_e32 v4, v1, v0
	v_mad_i64_i32 v[0:1], s[6:7], s8, v204, v[2:3]
	flat_store_dword v[0:1], v4
	s_branch .LBB0_2633
